# SCALE epilogue (out-proj and FFN-down GEMMs) rewritten with the full-128-byte-line store form (wave owns 64 contiguous columns, even/odd lane exchange)
# speedup vs baseline: 1.0024x; 1.0024x over previous
.LBB0_121:
	s_add_i32 m0, s3, 0x18000
	v_lshl_add_u64 v[10:11], v[10:11], 0, s[4:5]
	s_waitcnt vmcnt(2)
	s_barrier
	global_load_lds_dwordx4 v[10:11], off
	v_lshl_add_u64 v[6:7], v[6:7], 0, s[4:5]
	s_add_i32 m0, s3, 0x1a000
	s_add_i32 s80, s3, 0x8000
	global_load_lds_dwordx4 v[6:7], off
	v_lshl_add_u64 v[6:7], v[8:9], 0, s[4:5]
	s_mov_b32 m0, s80
	s_add_i32 s84, s3, 0xa000
	global_load_lds_dwordx4 v[6:7], off
	v_lshl_add_u64 v[6:7], v[12:13], 0, s[4:5]
	s_mov_b32 m0, s84
	v_lshl_add_u64 v[4:5], v[4:5], 0, s[4:5]
	global_load_lds_dwordx4 v[6:7], off
	s_add_i32 m0, s3, 0x1c000
	v_lshl_add_u64 v[2:3], v[2:3], 0, s[4:5]
	global_load_lds_dwordx4 v[4:5], off
	s_add_i32 m0, s3, 0x1e000
	s_lshl_b32 s11, s11, 5
	global_load_lds_dwordx4 v[2:3], off
	v_lshrrev_b32_e32 v2, 1, v15
	v_and_b32_e32 v2, 24, v2
	s_and_b32 s34, s11, 0x60
	v_and_b32_e32 v1, 15, v15
	v_lshlrev_b32_e32 v3, 1, v2
	v_or_b32_e32 v172, s34, v2
	v_rcp_iflag_f32_e32 v2, v14
	v_lshlrev_b32_e32 v241, 2, v1
	s_lshr_b32 s83, s10, 6
	v_lshl_or_b32 v3, v1, 6, v3
	v_and_b32_e32 v4, 32, v241
	s_mov_b32 s100, 0x14000
	s_mov_b32 s11, 7
	s_cmp_eq_u32 s81, 0
	s_cbranch_scc1 .Lfl_remap
	s_cmp_eq_u32 s81, 3
	s_cbranch_scc1 .Lfl_remap
	s_branch .Lfl_noremap

.LBB0_172:
	s_ashr_i32 s38, s69, 3
	s_mul_hi_i32 s39, s38, 0x6000
	s_mulk_i32 s38, 0x6000
	s_add_u32 s38, s26, s38
	s_addc_u32 s39, s27, s39
	v_and_b32_e32 v130, 1, v180
	v_and_b32_e32 v131, -2, v180
	v_bfe_u32 v132, v163, 4, 2
	v_bfe_u32 v133, v163, 6, 2
	v_lshlrev_b32_e32 v132, 3, v132
	v_lshl_add_u32 v132, v133, 6, v132
	s_lshl_b32 s44, s54, 8
	v_add_u32_e32 v136, s44, v132
	v_mov_b32_e32 v137, 0
	v_lshl_add_u64 v[138:139], v[136:137], 2, s[38:39]
	global_load_dwordx4 v[140:143], v[138:139], off
	global_load_dwordx4 v[144:147], v[138:139], off offset:16
	global_load_dwordx4 v[148:151], v[138:139], off offset:128
	global_load_dwordx4 v[152:155], v[138:139], off offset:144
	v_lshl_add_u32 v134, v130, 5, v136
	v_lshl_add_u32 v134, v131, 10, v134
	v_mov_b32_e32 v135, 0
	v_lshl_add_u64 v[134:135], v[134:135], 1, s[18:19]
	s_mov_b64 s[56:57], 0x800
	s_mov_b64 s[44:45], 0x8000
	s_mov_b32 vcc_lo, 0x55555555
	s_mov_b32 vcc_hi, 0x55555555
	s_waitcnt vmcnt(0)
	v_pk_mul_f32 v[126:127], v[126:127], v[140:141]
	v_pk_mul_f32 v[128:129], v[128:129], v[142:143]
	v_pk_mul_f32 v[122:123], v[122:123], v[144:145]
	v_pk_mul_f32 v[124:125], v[124:125], v[146:147]
	v_pk_mul_f32 v[118:119], v[118:119], v[148:149]
	v_pk_mul_f32 v[120:121], v[120:121], v[150:151]
	v_pk_mul_f32 v[114:115], v[114:115], v[152:153]
	v_pk_mul_f32 v[116:117], v[116:117], v[154:155]
	v_cvt_pk_bf16_f32 v196, v126, v127
	v_cvt_pk_bf16_f32 v197, v128, v129
	v_cvt_pk_bf16_f32 v198, v122, v123
	v_cvt_pk_bf16_f32 v199, v124, v125
	v_cvt_pk_bf16_f32 v200, v118, v119
	v_cvt_pk_bf16_f32 v201, v120, v121
	v_cvt_pk_bf16_f32 v202, v114, v115
	v_cvt_pk_bf16_f32 v203, v116, v117
	v_lshl_add_u64 v[156:157], s[56:57], 0, v[134:135]
	v_cndmask_b32_dpp v212, v200, v196, vcc quad_perm:[1,0,3,2] row_mask:0xf bank_mask:0xf
	v_cndmask_b32_dpp v213, v201, v197, vcc quad_perm:[1,0,3,2] row_mask:0xf bank_mask:0xf
	v_cndmask_b32_dpp v214, v202, v198, vcc quad_perm:[1,0,3,2] row_mask:0xf bank_mask:0xf
	v_cndmask_b32_dpp v215, v203, v199, vcc quad_perm:[1,0,3,2] row_mask:0xf bank_mask:0xf
	s_not_b64 vcc, vcc
	global_store_dwordx4 v[134:135], v[212:215], off
	s_nop 0
	v_cndmask_b32_dpp v216, v196, v200, vcc quad_perm:[1,0,3,2] row_mask:0xf bank_mask:0xf
	v_cndmask_b32_dpp v217, v197, v201, vcc quad_perm:[1,0,3,2] row_mask:0xf bank_mask:0xf
	v_cndmask_b32_dpp v218, v198, v202, vcc quad_perm:[1,0,3,2] row_mask:0xf bank_mask:0xf
	v_cndmask_b32_dpp v219, v199, v203, vcc quad_perm:[1,0,3,2] row_mask:0xf bank_mask:0xf
	s_not_b64 vcc, vcc
	global_store_dwordx4 v[156:157], v[216:219], off
	v_lshl_add_u64 v[134:135], s[44:45], 0, v[134:135]
	v_pk_mul_f32 v[110:111], v[110:111], v[140:141]
	v_pk_mul_f32 v[112:113], v[112:113], v[142:143]
	v_pk_mul_f32 v[106:107], v[106:107], v[144:145]
	v_pk_mul_f32 v[108:109], v[108:109], v[146:147]
	v_pk_mul_f32 v[102:103], v[102:103], v[148:149]
	v_pk_mul_f32 v[104:105], v[104:105], v[150:151]
	v_pk_mul_f32 v[98:99], v[98:99], v[152:153]
	v_pk_mul_f32 v[100:101], v[100:101], v[154:155]
	v_cvt_pk_bf16_f32 v204, v110, v111
	v_cvt_pk_bf16_f32 v205, v112, v113
	v_cvt_pk_bf16_f32 v206, v106, v107
	v_cvt_pk_bf16_f32 v207, v108, v109
	v_cvt_pk_bf16_f32 v208, v102, v103
	v_cvt_pk_bf16_f32 v209, v104, v105
	v_cvt_pk_bf16_f32 v210, v98, v99
	v_cvt_pk_bf16_f32 v211, v100, v101
	v_lshl_add_u64 v[156:157], s[56:57], 0, v[134:135]
	v_cndmask_b32_dpp v220, v208, v204, vcc quad_perm:[1,0,3,2] row_mask:0xf bank_mask:0xf
	v_cndmask_b32_dpp v221, v209, v205, vcc quad_perm:[1,0,3,2] row_mask:0xf bank_mask:0xf
	v_cndmask_b32_dpp v222, v210, v206, vcc quad_perm:[1,0,3,2] row_mask:0xf bank_mask:0xf
	v_cndmask_b32_dpp v223, v211, v207, vcc quad_perm:[1,0,3,2] row_mask:0xf bank_mask:0xf
	s_not_b64 vcc, vcc
	global_store_dwordx4 v[134:135], v[220:223], off
	s_nop 0
	v_cndmask_b32_dpp v224, v204, v208, vcc quad_perm:[1,0,3,2] row_mask:0xf bank_mask:0xf
	v_cndmask_b32_dpp v225, v205, v209, vcc quad_perm:[1,0,3,2] row_mask:0xf bank_mask:0xf
	v_cndmask_b32_dpp v226, v206, v210, vcc quad_perm:[1,0,3,2] row_mask:0xf bank_mask:0xf
	v_cndmask_b32_dpp v227, v207, v211, vcc quad_perm:[1,0,3,2] row_mask:0xf bank_mask:0xf
	s_not_b64 vcc, vcc
	global_store_dwordx4 v[156:157], v[224:227], off
	v_lshl_add_u64 v[134:135], s[44:45], 0, v[134:135]
	v_pk_mul_f32 v[94:95], v[94:95], v[140:141]
	v_pk_mul_f32 v[96:97], v[96:97], v[142:143]
	v_pk_mul_f32 v[90:91], v[90:91], v[144:145]
	v_pk_mul_f32 v[92:93], v[92:93], v[146:147]
	v_pk_mul_f32 v[86:87], v[86:87], v[148:149]
	v_pk_mul_f32 v[88:89], v[88:89], v[150:151]
	v_pk_mul_f32 v[82:83], v[82:83], v[152:153]
	v_pk_mul_f32 v[84:85], v[84:85], v[154:155]
	v_cvt_pk_bf16_f32 v196, v94, v95
	v_cvt_pk_bf16_f32 v197, v96, v97
	v_cvt_pk_bf16_f32 v198, v90, v91
	v_cvt_pk_bf16_f32 v199, v92, v93
	v_cvt_pk_bf16_f32 v200, v86, v87
	v_cvt_pk_bf16_f32 v201, v88, v89
	v_cvt_pk_bf16_f32 v202, v82, v83
	v_cvt_pk_bf16_f32 v203, v84, v85
	v_lshl_add_u64 v[156:157], s[56:57], 0, v[134:135]
	v_cndmask_b32_dpp v212, v200, v196, vcc quad_perm:[1,0,3,2] row_mask:0xf bank_mask:0xf
	v_cndmask_b32_dpp v213, v201, v197, vcc quad_perm:[1,0,3,2] row_mask:0xf bank_mask:0xf
	v_cndmask_b32_dpp v214, v202, v198, vcc quad_perm:[1,0,3,2] row_mask:0xf bank_mask:0xf
	v_cndmask_b32_dpp v215, v203, v199, vcc quad_perm:[1,0,3,2] row_mask:0xf bank_mask:0xf
	s_not_b64 vcc, vcc
	global_store_dwordx4 v[134:135], v[212:215], off
	s_nop 0
	v_cndmask_b32_dpp v216, v196, v200, vcc quad_perm:[1,0,3,2] row_mask:0xf bank_mask:0xf
	v_cndmask_b32_dpp v217, v197, v201, vcc quad_perm:[1,0,3,2] row_mask:0xf bank_mask:0xf
	v_cndmask_b32_dpp v218, v198, v202, vcc quad_perm:[1,0,3,2] row_mask:0xf bank_mask:0xf
	v_cndmask_b32_dpp v219, v199, v203, vcc quad_perm:[1,0,3,2] row_mask:0xf bank_mask:0xf
	s_not_b64 vcc, vcc
	global_store_dwordx4 v[156:157], v[216:219], off
	v_lshl_add_u64 v[134:135], s[44:45], 0, v[134:135]
	v_pk_mul_f32 v[78:79], v[78:79], v[140:141]
	v_pk_mul_f32 v[80:81], v[80:81], v[142:143]
	v_pk_mul_f32 v[74:75], v[74:75], v[144:145]
	v_pk_mul_f32 v[76:77], v[76:77], v[146:147]
	v_pk_mul_f32 v[70:71], v[70:71], v[148:149]
	v_pk_mul_f32 v[72:73], v[72:73], v[150:151]
	v_pk_mul_f32 v[66:67], v[66:67], v[152:153]
	v_pk_mul_f32 v[68:69], v[68:69], v[154:155]
	v_cvt_pk_bf16_f32 v204, v78, v79
	v_cvt_pk_bf16_f32 v205, v80, v81
	v_cvt_pk_bf16_f32 v206, v74, v75
	v_cvt_pk_bf16_f32 v207, v76, v77
	v_cvt_pk_bf16_f32 v208, v70, v71
	v_cvt_pk_bf16_f32 v209, v72, v73
	v_cvt_pk_bf16_f32 v210, v66, v67
	v_cvt_pk_bf16_f32 v211, v68, v69
	v_lshl_add_u64 v[156:157], s[56:57], 0, v[134:135]
	v_cndmask_b32_dpp v220, v208, v204, vcc quad_perm:[1,0,3,2] row_mask:0xf bank_mask:0xf
	v_cndmask_b32_dpp v221, v209, v205, vcc quad_perm:[1,0,3,2] row_mask:0xf bank_mask:0xf
	v_cndmask_b32_dpp v222, v210, v206, vcc quad_perm:[1,0,3,2] row_mask:0xf bank_mask:0xf
	v_cndmask_b32_dpp v223, v211, v207, vcc quad_perm:[1,0,3,2] row_mask:0xf bank_mask:0xf
	s_not_b64 vcc, vcc
	global_store_dwordx4 v[134:135], v[220:223], off
	s_nop 0
	v_cndmask_b32_dpp v224, v204, v208, vcc quad_perm:[1,0,3,2] row_mask:0xf bank_mask:0xf
	v_cndmask_b32_dpp v225, v205, v209, vcc quad_perm:[1,0,3,2] row_mask:0xf bank_mask:0xf
	v_cndmask_b32_dpp v226, v206, v210, vcc quad_perm:[1,0,3,2] row_mask:0xf bank_mask:0xf
	v_cndmask_b32_dpp v227, v207, v211, vcc quad_perm:[1,0,3,2] row_mask:0xf bank_mask:0xf
	s_not_b64 vcc, vcc
	global_store_dwordx4 v[156:157], v[224:227], off
	v_lshl_add_u64 v[134:135], s[44:45], 0, v[134:135]
	v_lshl_add_u64 v[134:135], s[44:45], 0, v[134:135]
	v_lshl_add_u64 v[134:135], s[44:45], 0, v[134:135]
	v_lshl_add_u64 v[134:135], s[44:45], 0, v[134:135]
	v_lshl_add_u64 v[134:135], s[44:45], 0, v[134:135]
	v_pk_mul_f32 v[62:63], v[62:63], v[140:141]
	v_pk_mul_f32 v[64:65], v[64:65], v[142:143]
	v_pk_mul_f32 v[58:59], v[58:59], v[144:145]
	v_pk_mul_f32 v[60:61], v[60:61], v[146:147]
	v_pk_mul_f32 v[54:55], v[54:55], v[148:149]
	v_pk_mul_f32 v[56:57], v[56:57], v[150:151]
	v_pk_mul_f32 v[50:51], v[50:51], v[152:153]
	v_pk_mul_f32 v[52:53], v[52:53], v[154:155]
	v_cvt_pk_bf16_f32 v196, v62, v63
	v_cvt_pk_bf16_f32 v197, v64, v65
	v_cvt_pk_bf16_f32 v198, v58, v59
	v_cvt_pk_bf16_f32 v199, v60, v61
	v_cvt_pk_bf16_f32 v200, v54, v55
	v_cvt_pk_bf16_f32 v201, v56, v57
	v_cvt_pk_bf16_f32 v202, v50, v51
	v_cvt_pk_bf16_f32 v203, v52, v53
	v_lshl_add_u64 v[156:157], s[56:57], 0, v[134:135]
	v_cndmask_b32_dpp v212, v200, v196, vcc quad_perm:[1,0,3,2] row_mask:0xf bank_mask:0xf
	v_cndmask_b32_dpp v213, v201, v197, vcc quad_perm:[1,0,3,2] row_mask:0xf bank_mask:0xf
	v_cndmask_b32_dpp v214, v202, v198, vcc quad_perm:[1,0,3,2] row_mask:0xf bank_mask:0xf
	v_cndmask_b32_dpp v215, v203, v199, vcc quad_perm:[1,0,3,2] row_mask:0xf bank_mask:0xf
	s_not_b64 vcc, vcc
	global_store_dwordx4 v[134:135], v[212:215], off
	s_nop 0
	v_cndmask_b32_dpp v216, v196, v200, vcc quad_perm:[1,0,3,2] row_mask:0xf bank_mask:0xf
	v_cndmask_b32_dpp v217, v197, v201, vcc quad_perm:[1,0,3,2] row_mask:0xf bank_mask:0xf
	v_cndmask_b32_dpp v218, v198, v202, vcc quad_perm:[1,0,3,2] row_mask:0xf bank_mask:0xf
	v_cndmask_b32_dpp v219, v199, v203, vcc quad_perm:[1,0,3,2] row_mask:0xf bank_mask:0xf
	s_not_b64 vcc, vcc
	global_store_dwordx4 v[156:157], v[216:219], off
	v_lshl_add_u64 v[134:135], s[44:45], 0, v[134:135]
	v_pk_mul_f32 v[46:47], v[46:47], v[140:141]
	v_pk_mul_f32 v[48:49], v[48:49], v[142:143]
	v_pk_mul_f32 v[42:43], v[42:43], v[144:145]
	v_pk_mul_f32 v[44:45], v[44:45], v[146:147]
	v_pk_mul_f32 v[38:39], v[38:39], v[148:149]
	v_pk_mul_f32 v[40:41], v[40:41], v[150:151]
	v_pk_mul_f32 v[34:35], v[34:35], v[152:153]
	v_pk_mul_f32 v[36:37], v[36:37], v[154:155]
	v_cvt_pk_bf16_f32 v204, v46, v47
	v_cvt_pk_bf16_f32 v205, v48, v49
	v_cvt_pk_bf16_f32 v206, v42, v43
	v_cvt_pk_bf16_f32 v207, v44, v45
	v_cvt_pk_bf16_f32 v208, v38, v39
	v_cvt_pk_bf16_f32 v209, v40, v41
	v_cvt_pk_bf16_f32 v210, v34, v35
	v_cvt_pk_bf16_f32 v211, v36, v37
	v_lshl_add_u64 v[156:157], s[56:57], 0, v[134:135]
	v_cndmask_b32_dpp v220, v208, v204, vcc quad_perm:[1,0,3,2] row_mask:0xf bank_mask:0xf
	v_cndmask_b32_dpp v221, v209, v205, vcc quad_perm:[1,0,3,2] row_mask:0xf bank_mask:0xf
	v_cndmask_b32_dpp v222, v210, v206, vcc quad_perm:[1,0,3,2] row_mask:0xf bank_mask:0xf
	v_cndmask_b32_dpp v223, v211, v207, vcc quad_perm:[1,0,3,2] row_mask:0xf bank_mask:0xf
	s_not_b64 vcc, vcc
	global_store_dwordx4 v[134:135], v[220:223], off
	s_nop 0
	v_cndmask_b32_dpp v224, v204, v208, vcc quad_perm:[1,0,3,2] row_mask:0xf bank_mask:0xf
	v_cndmask_b32_dpp v225, v205, v209, vcc quad_perm:[1,0,3,2] row_mask:0xf bank_mask:0xf
	v_cndmask_b32_dpp v226, v206, v210, vcc quad_perm:[1,0,3,2] row_mask:0xf bank_mask:0xf
	v_cndmask_b32_dpp v227, v207, v211, vcc quad_perm:[1,0,3,2] row_mask:0xf bank_mask:0xf
	s_not_b64 vcc, vcc
	global_store_dwordx4 v[156:157], v[224:227], off
	v_lshl_add_u64 v[134:135], s[44:45], 0, v[134:135]
	v_pk_mul_f32 v[30:31], v[30:31], v[140:141]
	v_pk_mul_f32 v[32:33], v[32:33], v[142:143]
	v_pk_mul_f32 v[26:27], v[26:27], v[144:145]
	v_pk_mul_f32 v[28:29], v[28:29], v[146:147]
	v_pk_mul_f32 v[22:23], v[22:23], v[148:149]
	v_pk_mul_f32 v[24:25], v[24:25], v[150:151]
	v_pk_mul_f32 v[18:19], v[18:19], v[152:153]
	v_pk_mul_f32 v[20:21], v[20:21], v[154:155]
	v_cvt_pk_bf16_f32 v196, v30, v31
	v_cvt_pk_bf16_f32 v197, v32, v33
	v_cvt_pk_bf16_f32 v198, v26, v27
	v_cvt_pk_bf16_f32 v199, v28, v29
	v_cvt_pk_bf16_f32 v200, v22, v23
	v_cvt_pk_bf16_f32 v201, v24, v25
	v_cvt_pk_bf16_f32 v202, v18, v19
	v_cvt_pk_bf16_f32 v203, v20, v21
	v_lshl_add_u64 v[156:157], s[56:57], 0, v[134:135]
	v_cndmask_b32_dpp v212, v200, v196, vcc quad_perm:[1,0,3,2] row_mask:0xf bank_mask:0xf
	v_cndmask_b32_dpp v213, v201, v197, vcc quad_perm:[1,0,3,2] row_mask:0xf bank_mask:0xf
	v_cndmask_b32_dpp v214, v202, v198, vcc quad_perm:[1,0,3,2] row_mask:0xf bank_mask:0xf
	v_cndmask_b32_dpp v215, v203, v199, vcc quad_perm:[1,0,3,2] row_mask:0xf bank_mask:0xf
	s_not_b64 vcc, vcc
	global_store_dwordx4 v[134:135], v[212:215], off
	s_nop 0
	v_cndmask_b32_dpp v216, v196, v200, vcc quad_perm:[1,0,3,2] row_mask:0xf bank_mask:0xf
	v_cndmask_b32_dpp v217, v197, v201, vcc quad_perm:[1,0,3,2] row_mask:0xf bank_mask:0xf
	v_cndmask_b32_dpp v218, v198, v202, vcc quad_perm:[1,0,3,2] row_mask:0xf bank_mask:0xf
	v_cndmask_b32_dpp v219, v199, v203, vcc quad_perm:[1,0,3,2] row_mask:0xf bank_mask:0xf
	s_not_b64 vcc, vcc
	global_store_dwordx4 v[156:157], v[216:219], off
	v_lshl_add_u64 v[134:135], s[44:45], 0, v[134:135]
	v_pk_mul_f32 v[14:15], v[14:15], v[140:141]
	v_pk_mul_f32 v[16:17], v[16:17], v[142:143]
	v_pk_mul_f32 v[10:11], v[10:11], v[144:145]
	v_pk_mul_f32 v[12:13], v[12:13], v[146:147]
	v_pk_mul_f32 v[6:7], v[6:7], v[148:149]
	v_pk_mul_f32 v[8:9], v[8:9], v[150:151]
	v_pk_mul_f32 v[2:3], v[2:3], v[152:153]
	v_pk_mul_f32 v[4:5], v[4:5], v[154:155]
	v_cvt_pk_bf16_f32 v204, v14, v15
	v_cvt_pk_bf16_f32 v205, v16, v17
	v_cvt_pk_bf16_f32 v206, v10, v11
	v_cvt_pk_bf16_f32 v207, v12, v13
	v_cvt_pk_bf16_f32 v208, v6, v7
	v_cvt_pk_bf16_f32 v209, v8, v9
	v_cvt_pk_bf16_f32 v210, v2, v3
	v_cvt_pk_bf16_f32 v211, v4, v5
	v_lshl_add_u64 v[156:157], s[56:57], 0, v[134:135]
	v_cndmask_b32_dpp v220, v208, v204, vcc quad_perm:[1,0,3,2] row_mask:0xf bank_mask:0xf
	v_cndmask_b32_dpp v221, v209, v205, vcc quad_perm:[1,0,3,2] row_mask:0xf bank_mask:0xf
	v_cndmask_b32_dpp v222, v210, v206, vcc quad_perm:[1,0,3,2] row_mask:0xf bank_mask:0xf
	v_cndmask_b32_dpp v223, v211, v207, vcc quad_perm:[1,0,3,2] row_mask:0xf bank_mask:0xf
	s_not_b64 vcc, vcc
	global_store_dwordx4 v[134:135], v[220:223], off
	s_nop 0
	v_cndmask_b32_dpp v224, v204, v208, vcc quad_perm:[1,0,3,2] row_mask:0xf bank_mask:0xf
	v_cndmask_b32_dpp v225, v205, v209, vcc quad_perm:[1,0,3,2] row_mask:0xf bank_mask:0xf
	v_cndmask_b32_dpp v226, v206, v210, vcc quad_perm:[1,0,3,2] row_mask:0xf bank_mask:0xf
	v_cndmask_b32_dpp v227, v207, v211, vcc quad_perm:[1,0,3,2] row_mask:0xf bank_mask:0xf
	s_not_b64 vcc, vcc
	global_store_dwordx4 v[156:157], v[224:227], off
	s_branch .LBB0_177
